# adds batched LDS fragment reads in the c3 stage-1 score MFMAs (all eight reads issued before the first MFMA, counted lgkmcnt waits) on top of the previous best
# speedup vs baseline: 1.0007x; 1.0007x over previous
; #define LAS __attribute__((address_space(3)))
; __device__ __forceinline__ bf16_t f2bf(float f) { return (bf16_t)(cvt_pk_bf16(f, 0.f) & 0xffffu); }
; __device__ __forceinline__ void phase_hgrn_c3(const Params& p, int l, int bid, int nblk, LAS unsigned char* lds) {
;     ...
;         for (int ti = 0; ti < 2; ++ti) {
;             const int tile = wid * 2 + ti, tt = tile >> 2, st = tile & 3;
;             f32x4 a4 = (f32x4){0.f, 0.f, 0.f, 0.f};
;             if (st <= tt) {
; #pragma unroll
;                 for (int ks = 0; ks < 4; ++ks) {
;                     const bf16x8 af = *(const LAS bf16x8*)(qA + (16 * tt + (lane & 15)) * 136 + ks * 32 + (lane >> 4) * 8);
;                     const bf16x8 bfr = *(const LAS bf16x8*)(kh + (16 * st + (lane & 15)) * 136 + ks * 32 + (lane >> 4) * 8);
;                     a4 = __builtin_amdgcn_mfma_f32_16x16x32_bf16(af, bfr, a4, 0, 0, 0);
;                 }
;             }
; #pragma unroll
;             for (int j = 0; j < 4; ++j) { const int t = 16 * tt + (lane >> 4) * 4 + j, s = 16 * st + (lane & 15); at[t * 72 + s] = f2bf(s <= t ? a4[j] : 0.f); }
;         }
.LBB0_245:
	v_mov_b32_e32 v26, 0
	v_mov_b32_e32 v28, 0
	v_mov_b32_e32 v29, 0
	v_mov_b32_e32 v30, 0
	v_mov_b32_e32 v31, 0
	s_waitcnt lgkmcnt(0)
	s_barrier
	s_and_saveexec_b64 s[38:39], s[14:15]
	s_cbranch_execz .LBB0_247
	ds_read_b128 v[28:31], v46
	ds_read_b128 v[188:191], v130 offset:34816
	ds_read_b128 v[192:195], v46 offset:64
	ds_read_b128 v[196:199], v130 offset:34880
	ds_read_b128 v[200:203], v46 offset:128
	ds_read_b128 v[204:207], v130 offset:34944
	ds_read_b128 v[208:211], v46 offset:192
	ds_read_b128 v[212:215], v130 offset:35008
	s_waitcnt lgkmcnt(6)
	v_mfma_f32_16x16x32_bf16 v[28:31], v[28:31], v[188:191], 0
	s_waitcnt lgkmcnt(4)
	v_mfma_f32_16x16x32_bf16 v[28:31], v[192:195], v[196:199], v[28:31]
	s_waitcnt lgkmcnt(2)
	v_mfma_f32_16x16x32_bf16 v[28:31], v[200:203], v[204:207], v[28:31]
	s_waitcnt lgkmcnt(0)
	v_mfma_f32_16x16x32_bf16 v[28:31], v[208:211], v[212:215], v[28:31]
.LBB0_247:
	s_or_b64 exec, exec, s[38:39]
	s_nop 6
	v_cndmask_b32_e64 v27, v28, 0, s[18:19]
	v_cvt_pk_bf16_f32 v27, v27, v5
	ds_write_b16 v127, v27
	v_cndmask_b32_e64 v27, v29, 0, s[20:21]
	v_cvt_pk_bf16_f32 v27, v27, v5
	ds_write_b16 v127, v27 offset:144
	v_cndmask_b32_e64 v27, v30, 0, s[22:23]
	v_cvt_pk_bf16_f32 v27, v27, v5
	ds_write_b16 v127, v27 offset:288
	v_cndmask_b32_e64 v27, v31, 0, s[24:25]
	v_cvt_pk_bf16_f32 v27, v27, v5
	ds_write_b16 v127, v27 offset:432
	v_mov_b32_e32 v27, 0
	v_mov_b32_e32 v28, 0
	v_mov_b32_e32 v29, 0
	s_and_saveexec_b64 s[38:39], s[16:17]
	s_cbranch_execz .LBB0_249
	ds_read_b128 v[26:29], v46
	ds_read_b128 v[188:191], v130 offset:39168
	ds_read_b128 v[192:195], v46 offset:64
	ds_read_b128 v[196:199], v130 offset:39232
	ds_read_b128 v[200:203], v46 offset:128
	ds_read_b128 v[204:207], v130 offset:39296
	ds_read_b128 v[208:211], v46 offset:192
	ds_read_b128 v[212:215], v130 offset:39360
	s_waitcnt lgkmcnt(6)
	v_mfma_f32_16x16x32_bf16 v[26:29], v[26:29], v[188:191], 0
	s_waitcnt lgkmcnt(4)
	v_mfma_f32_16x16x32_bf16 v[26:29], v[192:195], v[196:199], v[26:29]
	s_waitcnt lgkmcnt(2)
	v_mfma_f32_16x16x32_bf16 v[26:29], v[200:203], v[204:207], v[26:29]
	s_waitcnt lgkmcnt(0)
	v_mfma_f32_16x16x32_bf16 v[26:29], v[208:211], v[212:215], v[26:29]
